# phase-1 HX loop processes two rows per iteration: both rows' 32 loads are in flight together (was one row, one exposed HBM round trip per row)
# speedup vs baseline: 1.0046x; 1.0046x over previous
.LBB0_218:
	s_add_i32 s100, s40, s42
	s_cmpk_lt_i32 s100, 0x4400
	s_cbranch_scc0 .Lhx_single
	s_add_i32 s7, s40, 0xffffc000
	s_cmpk_lt_i32 s40, 0x4000
	s_cselect_b32 s9, s41, 0
	s_cselect_b32 s8, s40, s7
	s_cselect_b32 s7, s37, s39
	s_cselect_b32 s10, s36, s38
	s_lshl_b64 s[8:9], s[8:9], 12
	s_add_u32 s8, s10, s8
	s_addc_u32 s9, s7, s9
	global_load_dwordx4 v[16:19], v[4:5], off
	global_load_dwordx4 v[20:23], v[4:5], off offset:1024
	global_load_dwordx4 v[24:27], v[4:5], off offset:2048
	global_load_dwordx4 v[28:31], v[4:5], off offset:3072
	global_load_dwordx4 v[32:35], v11, s[8:9]
	global_load_dwordx4 v[36:39], v11, s[8:9] offset:1024
	global_load_dwordx4 v[40:43], v11, s[8:9] offset:2048
	global_load_dwordx4 v[44:47], v11, s[8:9] offset:3072
	s_min_i32 s7, s40, 0x4000
	s_ashr_i32 s7, s7, 12
	s_mul_hi_i32 s9, s7, 0x3000
	s_mulk_i32 s7, 0x3000
	s_add_u32 s8, s4, s7
	s_addc_u32 s9, s5, s9
	s_add_u32 s10, s8, 0x1000
	s_addc_u32 s11, s9, 0
	global_load_dwordx4 v[48:51], v11, s[8:9]
	global_load_dwordx4 v[52:55], v11, s[8:9] offset:1024
	global_load_dwordx4 v[56:59], v11, s[8:9] offset:2048
	global_load_dwordx4 v[60:63], v11, s[8:9] offset:3072
	global_load_dwordx4 v[64:67], v11, s[10:11]
	global_load_dwordx4 v[68:71], v13, s[10:11]
	global_load_dwordx4 v[72:75], v14, s[10:11]
	global_load_dwordx4 v[76:79], v15, s[10:11]
	s_add_u32 s40, s40, s42
	s_addc_u32 s41, s41, s43
	s_add_i32 s7, s40, 0xffffc000
	s_cmpk_lt_i32 s40, 0x4000
	s_cselect_b32 s9, s41, 0
	s_cselect_b32 s8, s40, s7
	s_cselect_b32 s7, s37, s39
	s_cselect_b32 s10, s36, s38
	s_lshl_b64 s[8:9], s[8:9], 12
	s_add_u32 s8, s10, s8
	s_addc_u32 s9, s7, s9
	global_load_dwordx4 v[124:127], v[4:5], off
	global_load_dwordx4 v[128:131], v[4:5], off offset:1024
	global_load_dwordx4 v[132:135], v[4:5], off offset:2048
	global_load_dwordx4 v[136:139], v[4:5], off offset:3072
	global_load_dwordx4 v[140:143], v11, s[8:9]
	global_load_dwordx4 v[144:147], v11, s[8:9] offset:1024
	global_load_dwordx4 v[148:151], v11, s[8:9] offset:2048
	global_load_dwordx4 v[152:155], v11, s[8:9] offset:3072
	s_min_i32 s7, s40, 0x4000
	s_ashr_i32 s7, s7, 12
	s_mul_hi_i32 s9, s7, 0x3000
	s_mulk_i32 s7, 0x3000
	s_add_u32 s8, s4, s7
	s_addc_u32 s9, s5, s9
	s_add_u32 s10, s8, 0x1000
	s_addc_u32 s11, s9, 0
	global_load_dwordx4 v[156:159], v11, s[8:9]
	global_load_dwordx4 v[160:163], v11, s[8:9] offset:1024
	global_load_dwordx4 v[164:167], v11, s[8:9] offset:2048
	global_load_dwordx4 v[168:171], v11, s[8:9] offset:3072
	global_load_dwordx4 v[172:175], v11, s[10:11]
	global_load_dwordx4 v[176:179], v13, s[10:11]
	global_load_dwordx4 v[180:183], v14, s[10:11]
	global_load_dwordx4 v[184:187], v15, s[10:11]
	s_add_u32 s40, s40, s42
	s_addc_u32 s41, s41, s43
	s_waitcnt vmcnt(27)
	v_pk_mul_f32 v[80:81], v[34:35], v[34:35]
	v_pk_mul_f32 v[82:83], v[32:33], v[32:33]
	s_waitcnt vmcnt(26)
	v_pk_mul_f32 v[84:85], v[38:39], v[38:39]
	v_pk_mul_f32 v[86:87], v[36:37], v[36:37]
	v_pk_mov_b32 v[92:93], v[82:83], v[80:81] op_sel:[1,0]
	v_mov_b32_e32 v83, v81
	v_pk_mov_b32 v[80:81], v[86:87], v[84:85] op_sel:[1,0]
	v_mov_b32_e32 v87, v85
	s_waitcnt vmcnt(25)
	v_mul_f32_e32 v88, v40, v40
	v_mul_f32_e32 v90, v42, v42
	v_pk_add_f32 v[82:83], v[92:93], v[82:83]
	v_pk_add_f32 v[80:81], v[80:81], v[86:87]
	v_pk_fma_f32 v[84:85], v[40:41], v[40:41], v[88:89] op_sel_hi:[1,1,0]
	v_pk_fma_f32 v[88:89], v[42:43], v[42:43], v[90:91] op_sel_hi:[1,1,0]
	v_pk_add_f32 v[82:83], v[82:83], v[82:83] op_sel_hi:[0,1]
	v_pk_add_f32 v[80:81], v[80:81], v[80:81] op_sel_hi:[0,1]
	s_waitcnt vmcnt(24)
	v_mul_f32_e32 v84, v44, v44
	v_mul_f32_e32 v88, v45, v45
	v_mul_f32_e32 v82, v46, v46
	v_mul_f32_e32 v80, v47, v47
	v_pk_add_f32 v[84:85], v[84:85], v[88:89]
	v_pk_add_f32 v[80:81], v[82:83], v[80:81]
	s_waitcnt vmcnt(19)
	v_pk_add_f32 v[66:67], v[66:67], 1.0 op_sel_hi:[1,0]
	v_pk_add_f32 v[80:81], v[84:85], v[80:81]
	v_pk_add_f32 v[64:65], v[64:65], 1.0 op_sel_hi:[1,0]
	v_add_f32_e32 v80, v80, v81
	ds_bpermute_b32 v81, v1, v80
	s_waitcnt vmcnt(18)
	v_pk_add_f32 v[70:71], v[70:71], 1.0 op_sel_hi:[1,0]
	v_pk_add_f32 v[68:69], v[68:69], 1.0 op_sel_hi:[1,0]
	s_waitcnt vmcnt(17)
	v_pk_add_f32 v[74:75], v[74:75], 1.0 op_sel_hi:[1,0]
	v_pk_add_f32 v[72:73], v[72:73], 1.0 op_sel_hi:[1,0]
	s_waitcnt lgkmcnt(0)
	v_add_f32_e32 v80, v80, v81
	ds_bpermute_b32 v81, v6, v80
	s_waitcnt vmcnt(16)
	v_pk_add_f32 v[78:79], v[78:79], 1.0 op_sel_hi:[1,0]
	v_pk_add_f32 v[76:77], v[76:77], 1.0 op_sel_hi:[1,0]
	s_waitcnt lgkmcnt(0)
	v_add_f32_e32 v80, v80, v81
	ds_bpermute_b32 v81, v7, v80
	s_waitcnt lgkmcnt(0)
	v_add_f32_e32 v80, v80, v81
	ds_bpermute_b32 v81, v8, v80
	s_waitcnt lgkmcnt(0)
	v_add_f32_e32 v80, v80, v81
	ds_bpermute_b32 v81, v9, v80
	s_waitcnt lgkmcnt(0)
	v_add_f32_e32 v80, v80, v81
	ds_bpermute_b32 v81, v10, v80
	s_waitcnt lgkmcnt(0)
	v_add_f32_e32 v80, v80, v81
	v_fmamk_f32 v80, v80, 0x3a800000, v12
	v_mul_f32_e32 v81, 0x4b800000, v80
	v_cmp_gt_f32_e32 vcc, s6, v80
	s_nop 1
	v_cndmask_b32_e32 v80, v80, v81, vcc
	v_rsq_f32_e32 v80, v80
	s_nop 0
	v_mul_f32_e32 v81, 0x45800000, v80
	v_cndmask_b32_e32 v80, v80, v81, vcc
	v_pk_mul_f32 v[34:35], v[34:35], v[80:81] op_sel_hi:[1,0]
	v_pk_mul_f32 v[32:33], v[32:33], v[80:81] op_sel_hi:[1,0]
	v_pk_mul_f32 v[38:39], v[38:39], v[80:81] op_sel_hi:[1,0]
	v_pk_mul_f32 v[36:37], v[36:37], v[80:81] op_sel_hi:[1,0]
	v_pk_mul_f32 v[42:43], v[42:43], v[80:81] op_sel_hi:[1,0]
	v_pk_mul_f32 v[40:41], v[40:41], v[80:81] op_sel_hi:[1,0]
	v_pk_mul_f32 v[46:47], v[46:47], v[80:81] op_sel_hi:[1,0]
	v_pk_mul_f32 v[44:45], v[44:45], v[80:81] op_sel_hi:[1,0]
	v_pk_mul_f32 v[16:17], v[16:17], v[32:33]
	v_pk_mul_f32 v[18:19], v[18:19], v[34:35]
	v_pk_mul_f32 v[20:21], v[20:21], v[36:37]
	v_pk_mul_f32 v[22:23], v[22:23], v[38:39]
	v_pk_mul_f32 v[24:25], v[24:25], v[40:41]
	v_pk_mul_f32 v[26:27], v[26:27], v[42:43]
	v_pk_mul_f32 v[28:29], v[28:29], v[44:45]
	v_pk_mul_f32 v[30:31], v[30:31], v[46:47]
	v_pk_fma_f32 v[18:19], v[66:67], v[18:19], v[50:51]
	v_pk_fma_f32 v[16:17], v[64:65], v[16:17], v[48:49]
	v_pk_fma_f32 v[22:23], v[70:71], v[22:23], v[54:55]
	v_pk_fma_f32 v[20:21], v[68:69], v[20:21], v[52:53]
	v_pk_fma_f32 v[26:27], v[74:75], v[26:27], v[58:59]
	v_pk_fma_f32 v[24:25], v[72:73], v[24:25], v[56:57]
	v_pk_fma_f32 v[30:31], v[78:79], v[30:31], v[62:63]
	v_pk_fma_f32 v[28:29], v[76:77], v[28:29], v[60:61]
	v_cvt_pk_bf16_f32 v16, v16, v17
	v_cvt_pk_bf16_f32 v17, v18, v19
	v_cvt_pk_bf16_f32 v18, v20, v21
	v_cvt_pk_bf16_f32 v19, v22, v23
	v_cvt_pk_bf16_f32 v20, v24, v25
	v_cvt_pk_bf16_f32 v21, v26, v27
	v_cvt_pk_bf16_f32 v22, v28, v29
	v_cvt_pk_bf16_f32 v23, v30, v31
	global_store_dwordx2 v[2:3], v[16:17], off
	global_store_dwordx2 v[2:3], v[18:19], off offset:512
	global_store_dwordx2 v[2:3], v[20:21], off offset:1024
	global_store_dwordx2 v[2:3], v[22:23], off offset:1536
	v_lshl_add_u64 v[2:3], v[2:3], 0, s[0:1]
	s_waitcnt vmcnt(15)
	v_pk_mul_f32 v[188:189], v[142:143], v[142:143]
	v_pk_mul_f32 v[190:191], v[140:141], v[140:141]
	s_waitcnt vmcnt(14)
	v_pk_mul_f32 v[192:193], v[146:147], v[146:147]
	v_pk_mul_f32 v[194:195], v[144:145], v[144:145]
	v_pk_mov_b32 v[200:201], v[190:191], v[188:189] op_sel:[1,0]
	v_mov_b32_e32 v191, v189
	v_pk_mov_b32 v[188:189], v[194:195], v[192:193] op_sel:[1,0]
	v_mov_b32_e32 v195, v193
	s_waitcnt vmcnt(13)
	v_mul_f32_e32 v196, v148, v148
	v_mul_f32_e32 v198, v150, v150
	v_pk_add_f32 v[190:191], v[200:201], v[190:191]
	v_pk_add_f32 v[188:189], v[188:189], v[194:195]
	v_pk_fma_f32 v[192:193], v[148:149], v[148:149], v[196:197] op_sel_hi:[1,1,0]
	v_pk_fma_f32 v[196:197], v[150:151], v[150:151], v[198:199] op_sel_hi:[1,1,0]
	v_pk_add_f32 v[190:191], v[190:191], v[190:191] op_sel_hi:[0,1]
	v_pk_add_f32 v[188:189], v[188:189], v[188:189] op_sel_hi:[0,1]
	s_waitcnt vmcnt(12)
	v_mul_f32_e32 v192, v152, v152
	v_mul_f32_e32 v196, v153, v153
	v_mul_f32_e32 v190, v154, v154
	v_mul_f32_e32 v188, v155, v155
	v_pk_add_f32 v[192:193], v[192:193], v[196:197]
	v_pk_add_f32 v[188:189], v[190:191], v[188:189]
	s_waitcnt vmcnt(7)
	v_pk_add_f32 v[174:175], v[174:175], 1.0 op_sel_hi:[1,0]
	v_pk_add_f32 v[188:189], v[192:193], v[188:189]
	v_pk_add_f32 v[172:173], v[172:173], 1.0 op_sel_hi:[1,0]
	v_add_f32_e32 v188, v188, v189
	ds_bpermute_b32 v189, v1, v188
	s_waitcnt vmcnt(6)
	v_pk_add_f32 v[178:179], v[178:179], 1.0 op_sel_hi:[1,0]
	v_pk_add_f32 v[176:177], v[176:177], 1.0 op_sel_hi:[1,0]
	s_waitcnt vmcnt(5)
	v_pk_add_f32 v[182:183], v[182:183], 1.0 op_sel_hi:[1,0]
	v_pk_add_f32 v[180:181], v[180:181], 1.0 op_sel_hi:[1,0]
	s_waitcnt lgkmcnt(0)
	v_add_f32_e32 v188, v188, v189
	ds_bpermute_b32 v189, v6, v188
	s_waitcnt vmcnt(4)
	v_pk_add_f32 v[186:187], v[186:187], 1.0 op_sel_hi:[1,0]
	v_pk_add_f32 v[184:185], v[184:185], 1.0 op_sel_hi:[1,0]
	s_waitcnt lgkmcnt(0)
	v_add_f32_e32 v188, v188, v189
	ds_bpermute_b32 v189, v7, v188
	s_waitcnt lgkmcnt(0)
	v_add_f32_e32 v188, v188, v189
	ds_bpermute_b32 v189, v8, v188
	s_waitcnt lgkmcnt(0)
	v_add_f32_e32 v188, v188, v189
	ds_bpermute_b32 v189, v9, v188
	s_waitcnt lgkmcnt(0)
	v_add_f32_e32 v188, v188, v189
	ds_bpermute_b32 v189, v10, v188
	s_waitcnt lgkmcnt(0)
	v_add_f32_e32 v188, v188, v189
	v_fmamk_f32 v188, v188, 0x3a800000, v12
	v_mul_f32_e32 v189, 0x4b800000, v188
	v_cmp_gt_f32_e32 vcc, s6, v188
	s_nop 1
	v_cndmask_b32_e32 v188, v188, v189, vcc
	v_rsq_f32_e32 v188, v188
	s_nop 0
	v_mul_f32_e32 v189, 0x45800000, v188
	v_cndmask_b32_e32 v188, v188, v189, vcc
	v_pk_mul_f32 v[142:143], v[142:143], v[188:189] op_sel_hi:[1,0]
	v_pk_mul_f32 v[140:141], v[140:141], v[188:189] op_sel_hi:[1,0]
	v_pk_mul_f32 v[146:147], v[146:147], v[188:189] op_sel_hi:[1,0]
	v_pk_mul_f32 v[144:145], v[144:145], v[188:189] op_sel_hi:[1,0]
	v_pk_mul_f32 v[150:151], v[150:151], v[188:189] op_sel_hi:[1,0]
	v_pk_mul_f32 v[148:149], v[148:149], v[188:189] op_sel_hi:[1,0]
	v_pk_mul_f32 v[154:155], v[154:155], v[188:189] op_sel_hi:[1,0]
	v_pk_mul_f32 v[152:153], v[152:153], v[188:189] op_sel_hi:[1,0]
	v_pk_mul_f32 v[124:125], v[124:125], v[140:141]
	v_pk_mul_f32 v[126:127], v[126:127], v[142:143]
	v_pk_mul_f32 v[128:129], v[128:129], v[144:145]
	v_pk_mul_f32 v[130:131], v[130:131], v[146:147]
	v_pk_mul_f32 v[132:133], v[132:133], v[148:149]
	v_pk_mul_f32 v[134:135], v[134:135], v[150:151]
	v_pk_mul_f32 v[136:137], v[136:137], v[152:153]
	v_pk_mul_f32 v[138:139], v[138:139], v[154:155]
	v_pk_fma_f32 v[126:127], v[174:175], v[126:127], v[158:159]
	v_pk_fma_f32 v[124:125], v[172:173], v[124:125], v[156:157]
	v_pk_fma_f32 v[130:131], v[178:179], v[130:131], v[162:163]
	v_pk_fma_f32 v[128:129], v[176:177], v[128:129], v[160:161]
	v_pk_fma_f32 v[134:135], v[182:183], v[134:135], v[166:167]
	v_pk_fma_f32 v[132:133], v[180:181], v[132:133], v[164:165]
	v_pk_fma_f32 v[138:139], v[186:187], v[138:139], v[170:171]
	v_pk_fma_f32 v[136:137], v[184:185], v[136:137], v[168:169]
	v_cvt_pk_bf16_f32 v124, v124, v125
	v_cvt_pk_bf16_f32 v125, v126, v127
	v_cvt_pk_bf16_f32 v126, v128, v129
	v_cvt_pk_bf16_f32 v127, v130, v131
	v_cvt_pk_bf16_f32 v128, v132, v133
	v_cvt_pk_bf16_f32 v129, v134, v135
	v_cvt_pk_bf16_f32 v130, v136, v137
	v_cvt_pk_bf16_f32 v131, v138, v139
	global_store_dwordx2 v[2:3], v[124:125], off
	global_store_dwordx2 v[2:3], v[126:127], off offset:512
	global_store_dwordx2 v[2:3], v[128:129], off offset:1024
	global_store_dwordx2 v[2:3], v[130:131], off offset:1536
	v_lshl_add_u64 v[2:3], v[2:3], 0, s[0:1]
	s_cmpk_lt_i32 s40, 0x4400
	s_cbranch_scc1 .LBB0_218
	s_branch .Lhx_done
.Lhx_single:
	s_add_i32 s7, s40, 0xffffc000
	s_cmpk_lt_i32 s40, 0x4000
	s_cselect_b32 s9, s41, 0
	s_cselect_b32 s8, s40, s7
	s_cselect_b32 s7, s37, s39
	s_cselect_b32 s10, s36, s38
	s_lshl_b64 s[8:9], s[8:9], 12
	s_add_u32 s8, s10, s8
	s_addc_u32 s9, s7, s9
	global_load_dwordx4 v[16:19], v[4:5], off
	global_load_dwordx4 v[20:23], v[4:5], off offset:1024
	global_load_dwordx4 v[24:27], v[4:5], off offset:2048
	global_load_dwordx4 v[28:31], v[4:5], off offset:3072
	global_load_dwordx4 v[32:35], v11, s[8:9]
	global_load_dwordx4 v[36:39], v11, s[8:9] offset:1024
	global_load_dwordx4 v[40:43], v11, s[8:9] offset:2048
	global_load_dwordx4 v[44:47], v11, s[8:9] offset:3072
	s_min_i32 s7, s40, 0x4000
	s_ashr_i32 s7, s7, 12
	s_mul_hi_i32 s9, s7, 0x3000
	s_mulk_i32 s7, 0x3000
	s_add_u32 s8, s4, s7
	s_addc_u32 s9, s5, s9
	s_add_u32 s10, s8, 0x1000
	s_addc_u32 s11, s9, 0
	global_load_dwordx4 v[48:51], v11, s[8:9]
	global_load_dwordx4 v[52:55], v11, s[8:9] offset:1024
	global_load_dwordx4 v[56:59], v11, s[8:9] offset:2048
	global_load_dwordx4 v[60:63], v11, s[8:9] offset:3072
	global_load_dwordx4 v[64:67], v11, s[10:11]
	global_load_dwordx4 v[68:71], v13, s[10:11]
	global_load_dwordx4 v[72:75], v14, s[10:11]
	global_load_dwordx4 v[76:79], v15, s[10:11]
	s_add_u32 s40, s40, s42
	s_addc_u32 s41, s41, s43
	s_waitcnt vmcnt(11)
	v_pk_mul_f32 v[80:81], v[34:35], v[34:35]
	v_pk_mul_f32 v[82:83], v[32:33], v[32:33]
	s_waitcnt vmcnt(10)
	v_pk_mul_f32 v[84:85], v[38:39], v[38:39]
	v_pk_mul_f32 v[86:87], v[36:37], v[36:37]
	v_pk_mov_b32 v[92:93], v[82:83], v[80:81] op_sel:[1,0]
	v_mov_b32_e32 v83, v81
	v_pk_mov_b32 v[80:81], v[86:87], v[84:85] op_sel:[1,0]
	v_mov_b32_e32 v87, v85
	s_waitcnt vmcnt(9)
	v_mul_f32_e32 v88, v40, v40
	v_mul_f32_e32 v90, v42, v42
	v_pk_add_f32 v[82:83], v[92:93], v[82:83]
	v_pk_add_f32 v[80:81], v[80:81], v[86:87]
	v_pk_fma_f32 v[84:85], v[40:41], v[40:41], v[88:89] op_sel_hi:[1,1,0]
	v_pk_fma_f32 v[88:89], v[42:43], v[42:43], v[90:91] op_sel_hi:[1,1,0]
	v_pk_add_f32 v[82:83], v[82:83], v[82:83] op_sel_hi:[0,1]
	v_pk_add_f32 v[80:81], v[80:81], v[80:81] op_sel_hi:[0,1]
	s_waitcnt vmcnt(8)
	v_mul_f32_e32 v84, v44, v44
	v_mul_f32_e32 v88, v45, v45
	v_mul_f32_e32 v82, v46, v46
	v_mul_f32_e32 v80, v47, v47
	v_pk_add_f32 v[84:85], v[84:85], v[88:89]
	v_pk_add_f32 v[80:81], v[82:83], v[80:81]
	s_waitcnt vmcnt(3)
	v_pk_add_f32 v[66:67], v[66:67], 1.0 op_sel_hi:[1,0]
	v_pk_add_f32 v[80:81], v[84:85], v[80:81]
	v_pk_add_f32 v[64:65], v[64:65], 1.0 op_sel_hi:[1,0]
	v_add_f32_e32 v80, v80, v81
	ds_bpermute_b32 v81, v1, v80
	s_waitcnt vmcnt(2)
	v_pk_add_f32 v[70:71], v[70:71], 1.0 op_sel_hi:[1,0]
	v_pk_add_f32 v[68:69], v[68:69], 1.0 op_sel_hi:[1,0]
	s_waitcnt vmcnt(1)
	v_pk_add_f32 v[74:75], v[74:75], 1.0 op_sel_hi:[1,0]
	v_pk_add_f32 v[72:73], v[72:73], 1.0 op_sel_hi:[1,0]
	s_waitcnt lgkmcnt(0)
	v_add_f32_e32 v80, v80, v81
	ds_bpermute_b32 v81, v6, v80
	s_waitcnt vmcnt(0)
	v_pk_add_f32 v[78:79], v[78:79], 1.0 op_sel_hi:[1,0]
	v_pk_add_f32 v[76:77], v[76:77], 1.0 op_sel_hi:[1,0]
	s_waitcnt lgkmcnt(0)
	v_add_f32_e32 v80, v80, v81
	ds_bpermute_b32 v81, v7, v80
	s_waitcnt lgkmcnt(0)
	v_add_f32_e32 v80, v80, v81
	ds_bpermute_b32 v81, v8, v80
	s_waitcnt lgkmcnt(0)
	v_add_f32_e32 v80, v80, v81
	ds_bpermute_b32 v81, v9, v80
	s_waitcnt lgkmcnt(0)
	v_add_f32_e32 v80, v80, v81
	ds_bpermute_b32 v81, v10, v80
	s_waitcnt lgkmcnt(0)
	v_add_f32_e32 v80, v80, v81
	v_fmamk_f32 v80, v80, 0x3a800000, v12
	v_mul_f32_e32 v81, 0x4b800000, v80
	v_cmp_gt_f32_e32 vcc, s6, v80
	s_nop 1
	v_cndmask_b32_e32 v80, v80, v81, vcc
	v_rsq_f32_e32 v80, v80
	s_nop 0
	v_mul_f32_e32 v81, 0x45800000, v80
	v_cndmask_b32_e32 v80, v80, v81, vcc
	v_pk_mul_f32 v[34:35], v[34:35], v[80:81] op_sel_hi:[1,0]
	v_pk_mul_f32 v[32:33], v[32:33], v[80:81] op_sel_hi:[1,0]
	v_pk_mul_f32 v[38:39], v[38:39], v[80:81] op_sel_hi:[1,0]
	v_pk_mul_f32 v[36:37], v[36:37], v[80:81] op_sel_hi:[1,0]
	v_pk_mul_f32 v[42:43], v[42:43], v[80:81] op_sel_hi:[1,0]
	v_pk_mul_f32 v[40:41], v[40:41], v[80:81] op_sel_hi:[1,0]
	v_pk_mul_f32 v[46:47], v[46:47], v[80:81] op_sel_hi:[1,0]
	v_pk_mul_f32 v[44:45], v[44:45], v[80:81] op_sel_hi:[1,0]
	v_pk_mul_f32 v[16:17], v[16:17], v[32:33]
	v_pk_mul_f32 v[18:19], v[18:19], v[34:35]
	v_pk_mul_f32 v[20:21], v[20:21], v[36:37]
	v_pk_mul_f32 v[22:23], v[22:23], v[38:39]
	v_pk_mul_f32 v[24:25], v[24:25], v[40:41]
	v_pk_mul_f32 v[26:27], v[26:27], v[42:43]
	v_pk_mul_f32 v[28:29], v[28:29], v[44:45]
	v_pk_mul_f32 v[30:31], v[30:31], v[46:47]
	v_pk_fma_f32 v[18:19], v[66:67], v[18:19], v[50:51]
	v_pk_fma_f32 v[16:17], v[64:65], v[16:17], v[48:49]
	v_pk_fma_f32 v[22:23], v[70:71], v[22:23], v[54:55]
	v_pk_fma_f32 v[20:21], v[68:69], v[20:21], v[52:53]
	v_pk_fma_f32 v[26:27], v[74:75], v[26:27], v[58:59]
	v_pk_fma_f32 v[24:25], v[72:73], v[24:25], v[56:57]
	v_pk_fma_f32 v[30:31], v[78:79], v[30:31], v[62:63]
	v_pk_fma_f32 v[28:29], v[76:77], v[28:29], v[60:61]
	v_cvt_pk_bf16_f32 v16, v16, v17
	v_cvt_pk_bf16_f32 v17, v18, v19
	v_cvt_pk_bf16_f32 v18, v20, v21
	v_cvt_pk_bf16_f32 v19, v22, v23
	v_cvt_pk_bf16_f32 v20, v24, v25
	v_cvt_pk_bf16_f32 v21, v26, v27
	v_cvt_pk_bf16_f32 v22, v28, v29
	v_cvt_pk_bf16_f32 v23, v30, v31
	global_store_dwordx2 v[2:3], v[16:17], off
	global_store_dwordx2 v[2:3], v[18:19], off offset:512
	global_store_dwordx2 v[2:3], v[20:21], off offset:1024
	global_store_dwordx2 v[2:3], v[22:23], off offset:1536
	v_lshl_add_u64 v[2:3], v[2:3], 0, s[0:1]
.Lhx_done:
.LBB0_219:
	s_cmp_eq_u32 s86, 0
	s_cselect_b64 s[0:1], -1, 0
	s_cmp_eq_u32 s85, 2
	s_cselect_b64 s[4:5], -1, 0
	s_or_b64 s[0:1], s[0:1], s[4:5]
	s_and_b64 vcc, exec, s[0:1]
	s_cbranch_vccnz .LBB0_285
	s_cmp_lg_u32 s86, 2
	s_mov_b64 s[0:1], -1
	s_cbranch_scc0 .LBB0_273
	s_waitcnt vmcnt(0)
	s_barrier
	s_mov_b64 s[0:1], exec
	v_readlane_b32 s4, v253, 2
	v_readlane_b32 s5, v253, 3
	s_and_b64 s[4:5], s[0:1], s[4:5]
	s_mov_b64 exec, s[4:5]
	s_cbranch_execz .LBB0_272
	s_add_i32 s4, 0, 0x27ff0
	v_mov_b32_e32 v1, s4
	s_waitcnt vmcnt(0) expcnt(0) lgkmcnt(0)
	ds_read_b32 v3, v1
	s_add_i32 s4, 0, 0x27ff4
	v_mov_b32_e32 v1, s4
	ds_read_b32 v1, v1
	s_mov_b32 s9, 0
	s_waitcnt lgkmcnt(1)
	v_cmp_ne_u32_e32 vcc, 0, v3
	s_cbranch_vccnz .LBB0_236
	v_readlane_b32 s6, v253, 4
	v_readlane_b32 s7, v253, 5
	s_load_dwordx2 s[4:5], s[6:7], 0x4
	s_lshl_b32 s10, s3, 8
	s_add_u32 s11, s14, 0x400
	s_addc_u32 s12, s15, 0
	v_mov_b32_e32 v2, 0
	s_waitcnt lgkmcnt(0)
	s_mul_i32 s13, s4, s33
	s_mul_i32 s13, s13, s5
	s_branch .LBB0_225
